# 7.3 widened epilogue stores also in the P2 GEMM epilogue (accumulators kept for the SSQ part)
# speedup vs baseline: 1.0193x; 1.0050x over previous
; DI unsigned pk2(float a, float b) { f2_t v = {a, b}; bf2_t r = __builtin_convertvector(v, bf2_t); return __builtin_bit_cast(unsigned, r); }
; DI void phase2(const Params& p, char* smem, int rep) {
;     ...
;     gemm_tile<true>(H, D_, W, D_, D_, tm * 128, tn * 128, smem, [&](f32x16 (&acc)[2][2], int mb, int nb, int r, int hi) __attribute__((always_inline)) {
; #pragma unroll
;       for (int mi = 0; mi < 2; ++mi)
; #pragma unroll
;         for (int ni = 0; ni < 2; ++ni)
; #pragma unroll
;           for (int g = 0; g < 4; ++g) {
;             const int row = mb + mi * 32 + r, col = nb + ni * 32 + hi * 4 + 8 * g;
;             *(uint2*)(P + (size_t)row * INC + col) = make_uint2(pk2(acc[mi][ni][4 * g], acc[mi][ni][4 * g + 1]), pk2(acc[mi][ni][4 * g + 2], acc[mi][ni][4 * g + 3]));
;           }
;       if (nb >= 3072) {
; #pragma unroll
;         for (int mi = 0; mi < 2; ++mi) {
;           float ss = 0.f;
; #pragma unroll
;           for (int ni = 0; ni < 2; ++ni)
; #pragma unroll
;             for (int i = 0; i < 16; ++i) ss += acc[mi][ni][i] * acc[mi][ni][i];
;           ss += __shfl_xor(ss, 32);
;           if (hi == 0) SSQ[(size_t)(mb + mi * 32 + r) * 16 + ((nb - 3072) >> 6)] = ss;
;         }
;       }
;     });
.LBB0_393:
	v_or_b32_e32 v67, s23, v151
	v_or_b32_e32 v70, v67, v152
	v_add_u32_e32 v68, s22, v148
	v_mov_b64_e32 v[74:75], s[4:5]
	v_ashrrev_i32_e32 v71, 31, v70
	v_mad_i64_i32 v[76:77], s[10:11], v68, s19, v[74:75]
	v_lshlrev_b64 v[70:71], 1, v[70:71]
	v_and_b32_e32 v96, 32, v0
	v_lshrrev_b32_e32 v96, 2, v96
	v_mov_b32_e32 v97, 0
	v_lshl_add_u64 v[70:71], v[70:71], 0, v[96:97]
	v_lshl_add_u64 v[76:77], v[76:77], 0, v[70:71]
	v_or_b32_e32 v66, 32, v68
	v_mad_i64_i32 v[74:75], s[10:11], v66, s19, v[74:75]
	v_lshl_add_u64 v[98:99], v[74:75], 0, v[70:71]
	v_cvt_pk_bf16_f32 v80, v50, v51
	v_cvt_pk_bf16_f32 v81, v52, v53
	v_cvt_pk_bf16_f32 v82, v54, v55
	v_cvt_pk_bf16_f32 v83, v56, v57
	v_cvt_pk_bf16_f32 v84, v58, v59
	v_cvt_pk_bf16_f32 v85, v60, v61
	v_cvt_pk_bf16_f32 v86, v62, v63
	v_cvt_pk_bf16_f32 v87, v64, v65
	v_permlane32_swap_b32_e32 v80, v82
	v_permlane32_swap_b32_e32 v81, v83
	v_permlane32_swap_b32_e32 v84, v86
	v_permlane32_swap_b32_e32 v85, v87
	global_store_dwordx4 v[76:77], v[80:83], off
	global_store_dwordx4 v[76:77], v[84:87], off offset:32
	v_cvt_pk_bf16_f32 v88, v34, v35
	v_cvt_pk_bf16_f32 v89, v36, v37
	v_cvt_pk_bf16_f32 v90, v38, v39
	v_cvt_pk_bf16_f32 v91, v40, v41
	v_cvt_pk_bf16_f32 v92, v42, v43
	v_cvt_pk_bf16_f32 v93, v44, v45
	v_cvt_pk_bf16_f32 v94, v46, v47
	v_cvt_pk_bf16_f32 v95, v48, v49
	v_permlane32_swap_b32_e32 v88, v90
	v_permlane32_swap_b32_e32 v89, v91
	v_permlane32_swap_b32_e32 v92, v94
	v_permlane32_swap_b32_e32 v93, v95
	global_store_dwordx4 v[76:77], v[88:91], off offset:64
	global_store_dwordx4 v[76:77], v[92:95], off offset:96
	v_cvt_pk_bf16_f32 v80, v18, v19
	v_cvt_pk_bf16_f32 v81, v20, v21
	v_cvt_pk_bf16_f32 v82, v22, v23
	v_cvt_pk_bf16_f32 v83, v24, v25
	v_cvt_pk_bf16_f32 v84, v26, v27
	v_cvt_pk_bf16_f32 v85, v28, v29
	v_cvt_pk_bf16_f32 v86, v30, v31
	v_cvt_pk_bf16_f32 v87, v32, v33
	v_permlane32_swap_b32_e32 v80, v82
	v_permlane32_swap_b32_e32 v81, v83
	v_permlane32_swap_b32_e32 v84, v86
	v_permlane32_swap_b32_e32 v85, v87
	global_store_dwordx4 v[98:99], v[80:83], off
	global_store_dwordx4 v[98:99], v[84:87], off offset:32
	v_cvt_pk_bf16_f32 v88, v2, v3
	v_cvt_pk_bf16_f32 v89, v4, v5
	v_cvt_pk_bf16_f32 v90, v6, v7
	v_cvt_pk_bf16_f32 v91, v8, v9
	v_cvt_pk_bf16_f32 v92, v10, v11
	v_cvt_pk_bf16_f32 v93, v12, v13
	v_cvt_pk_bf16_f32 v94, v14, v15
	v_cvt_pk_bf16_f32 v95, v16, v17
	v_permlane32_swap_b32_e32 v88, v90
	v_permlane32_swap_b32_e32 v89, v91
	v_permlane32_swap_b32_e32 v92, v94
	v_permlane32_swap_b32_e32 v93, v95
	global_store_dwordx4 v[98:99], v[88:91], off offset:64
	global_store_dwordx4 v[98:99], v[92:95], off offset:96
	v_cmp_lt_i32_e32 vcc, s20, v67
	s_and_saveexec_b64 s[10:11], vcc
	s_cbranch_execz .LBB0_384
	v_mul_f32_e32 v51, v51, v51
	v_fmac_f32_e32 v51, v50, v50
	v_fmac_f32_e32 v51, v52, v52
	v_fmac_f32_e32 v51, v53, v53
	v_fmac_f32_e32 v51, v54, v54
	v_fmac_f32_e32 v51, v55, v55
	v_fmac_f32_e32 v51, v56, v56
	v_fmac_f32_e32 v51, v57, v57
	v_fmac_f32_e32 v51, v58, v58
	v_fmac_f32_e32 v51, v59, v59
	v_fmac_f32_e32 v51, v60, v60
	v_fmac_f32_e32 v51, v61, v61
	v_fmac_f32_e32 v51, v62, v62
	v_fmac_f32_e32 v51, v63, v63
	v_fmac_f32_e32 v51, v64, v64
	v_fmac_f32_e32 v51, v65, v65
	v_fmac_f32_e32 v51, v34, v34
	v_fmac_f32_e32 v51, v35, v35
	v_fmac_f32_e32 v51, v36, v36
	v_fmac_f32_e32 v51, v37, v37
	v_fmac_f32_e32 v51, v38, v38
	v_fmac_f32_e32 v51, v39, v39
	v_fmac_f32_e32 v51, v40, v40
	v_fmac_f32_e32 v51, v41, v41
	v_fmac_f32_e32 v51, v42, v42
	v_fmac_f32_e32 v51, v43, v43
	v_fmac_f32_e32 v51, v44, v44
	v_and_b32_e32 v70, 64, v153
	v_fmac_f32_e32 v51, v45, v45
	v_xor_b32_e32 v69, 32, v153
	v_add_u32_e32 v70, 64, v70
	v_fmac_f32_e32 v51, v46, v46
	v_cmp_lt_i32_e32 vcc, v69, v70
	v_fmac_f32_e32 v51, v47, v47
	v_fmac_f32_e32 v51, v48, v48
	v_cndmask_b32_e32 v69, v153, v69, vcc
	v_lshlrev_b32_e32 v70, 2, v69
	v_fmac_f32_e32 v51, v49, v49
	ds_bpermute_b32 v34, v70, v51
	v_add_u32_e32 v35, 0xfffff400, v67
	v_lshrrev_b32_e32 v35, 6, v35
	v_lshlrev_b32_e32 v130, 2, v35
	s_and_saveexec_b64 s[14:15], s[2:3]
	s_cbranch_execz .LBB0_396
	v_ashrrev_i32_e32 v69, 31, v68
	s_waitcnt lgkmcnt(0)
	v_add_f32_e32 v36, v51, v34
	v_lshlrev_b64 v[34:35], 6, v[68:69]
	v_lshl_add_u64 v[34:35], s[6:7], 0, v[34:35]
	v_lshl_add_u64 v[34:35], v[34:35], 0, v[130:131]
	global_store_dword v[34:35], v36, off
